# mixer fused epilogue (pool layers): the four pool_scale loads issued together before the residual-tile loads, one counted vmcnt(8) instead of two round trips ending in vmcnt(0)
# baseline (speedup 1.0000x reference)
.LBB0_594:
	v_bfe_u32 v96, v170, 4, 2
	s_mov_b64 s[2:3], s[0:1]
	s_barrier
	s_load_dwordx2 s[16:17], s[2:3], 0x88
	s_and_b32 s4, s41, 0x7fffffc
	s_load_dwordx2 s[2:3], s[2:3], 0x68
	v_readlane_b32 s20, v255, 14
	v_readlane_b32 s21, v255, 15
	s_waitcnt lgkmcnt(0)
	s_add_u32 s27, s16, 0x7000000
	s_addc_u32 s62, s17, 0
	s_cmp_eq_u32 s4, 4
	s_cselect_b32 s4, 0x2000000, 0
	s_add_u32 s6, s27, s4
	s_addc_u32 s7, s62, 0
	s_lshl_b32 s4, s14, 8
	s_lshl_b32 s26, s19, 5
	s_lshl_b32 s25, s34, 6
	s_add_i32 s26, s26, s4
	s_lshl_b32 s24, s18, 8
	v_add_u32_e32 v98, s25, v238
	v_lshl_add_u32 v224, v96, 3, s26
	v_add_u32_e32 v98, s24, v98
	v_ashrrev_i32_e32 v225, 31, v224
	v_ashrrev_i32_e32 v99, 31, v98
	v_lshl_add_u64 v[188:189], v[224:225], 1, s[6:7]
	v_lshlrev_b64 v[222:223], 11, v[98:99]
	s_cmp_eq_u64 s[2:3], 0
	s_cselect_b64 s[4:5], -1, 0
	s_or_b64 s[4:5], s[20:21], s[4:5]
	s_and_b64 vcc, exec, s[4:5]
	s_cbranch_vccnz .Lps_skip
	s_lshl_b32 s4, s36, 11
	s_and_b32 s4, s4, 0x1000
	s_add_u32 s2, s2, s4
	s_addc_u32 s3, s3, 0
	v_lshl_add_u64 v[168:169], v[224:225], 2, s[2:3]
	global_load_dwordx4 v[164:167], v[168:169], off offset:16
	global_load_dwordx4 v[172:175], v[168:169], off
	global_load_dwordx4 v[176:179], v[168:169], off offset:528
	global_load_dwordx4 v[180:183], v[168:169], off offset:512
.Lps_skip:
	v_lshl_add_u64 v[132:133], v[188:189], 0, v[222:223]
	global_load_dwordx4 v[160:163], v[132:133], off
	global_load_dwordx4 v[156:159], v[132:133], off offset:256
	v_add_u32_e32 v132, 16, v98
	v_ashrrev_i32_e32 v133, 31, v132
	v_lshlrev_b64 v[220:221], 11, v[132:133]
	v_lshl_add_u64 v[132:133], v[188:189], 0, v[220:221]
	global_load_dwordx4 v[152:155], v[132:133], off
	global_load_dwordx4 v[148:151], v[132:133], off offset:256
	v_add_u32_e32 v132, 32, v98
	v_ashrrev_i32_e32 v133, 31, v132
	v_lshlrev_b64 v[218:219], 11, v[132:133]
	v_lshl_add_u64 v[132:133], v[188:189], 0, v[218:219]
	global_load_dwordx4 v[144:147], v[132:133], off
	global_load_dwordx4 v[140:143], v[132:133], off offset:256
	v_add_u32_e32 v132, 48, v98
	v_ashrrev_i32_e32 v133, 31, v132
	v_lshlrev_b64 v[216:217], 11, v[132:133]
	v_lshl_add_u64 v[132:133], v[188:189], 0, v[216:217]
	global_load_dwordx4 v[136:139], v[132:133], off
	s_nop 0
	global_load_dwordx4 v[132:135], v[132:133], off offset:256
	s_cbranch_vccnz .LBB0_596
	s_waitcnt vmcnt(8)
	v_pk_mul_f32 v[126:127], v[126:127], v[166:167]
	v_pk_mul_f32 v[130:131], v[130:131], v[174:175]
	v_pk_mul_f32 v[128:129], v[128:129], v[172:173]
	v_pk_mul_f32 v[114:115], v[114:115], v[174:175]
	v_pk_mul_f32 v[112:113], v[112:113], v[172:173]
	v_pk_mul_f32 v[94:95], v[94:95], v[174:175]
	v_pk_mul_f32 v[92:93], v[92:93], v[172:173]
	v_pk_mul_f32 v[78:79], v[78:79], v[174:175]
	v_pk_mul_f32 v[76:77], v[76:77], v[172:173]
	v_pk_mul_f32 v[62:63], v[62:63], v[174:175]
	v_pk_mul_f32 v[60:61], v[60:61], v[172:173]
	v_pk_mul_f32 v[46:47], v[46:47], v[174:175]
	v_pk_mul_f32 v[44:45], v[44:45], v[172:173]
	v_pk_mul_f32 v[30:31], v[30:31], v[174:175]
	v_pk_mul_f32 v[28:29], v[28:29], v[172:173]
	v_pk_mul_f32 v[14:15], v[14:15], v[174:175]
	v_pk_mul_f32 v[12:13], v[12:13], v[172:173]
	v_pk_mul_f32 v[124:125], v[124:125], v[164:165]
	v_pk_mul_f32 v[110:111], v[110:111], v[166:167]
	v_pk_mul_f32 v[108:109], v[108:109], v[164:165]
	v_pk_mul_f32 v[90:91], v[90:91], v[166:167]
	v_pk_mul_f32 v[88:89], v[88:89], v[164:165]
	v_pk_mul_f32 v[74:75], v[74:75], v[166:167]
	v_pk_mul_f32 v[72:73], v[72:73], v[164:165]
	v_pk_mul_f32 v[58:59], v[58:59], v[166:167]
	v_pk_mul_f32 v[56:57], v[56:57], v[164:165]
	v_pk_mul_f32 v[42:43], v[42:43], v[166:167]
	v_pk_mul_f32 v[40:41], v[40:41], v[164:165]
	v_pk_mul_f32 v[26:27], v[26:27], v[166:167]
	v_pk_mul_f32 v[24:25], v[24:25], v[164:165]
	v_pk_mul_f32 v[10:11], v[10:11], v[166:167]
	v_pk_mul_f32 v[8:9], v[8:9], v[164:165]
	v_pk_mul_f32 v[118:119], v[118:119], v[178:179]
	v_pk_mul_f32 v[122:123], v[122:123], v[182:183]
	v_pk_mul_f32 v[120:121], v[120:121], v[180:181]
	v_pk_mul_f32 v[106:107], v[106:107], v[182:183]
	v_pk_mul_f32 v[104:105], v[104:105], v[180:181]
	v_pk_mul_f32 v[86:87], v[86:87], v[182:183]
	v_pk_mul_f32 v[84:85], v[84:85], v[180:181]
	v_pk_mul_f32 v[70:71], v[70:71], v[182:183]
	v_pk_mul_f32 v[68:69], v[68:69], v[180:181]
	v_pk_mul_f32 v[54:55], v[54:55], v[182:183]
	v_pk_mul_f32 v[52:53], v[52:53], v[180:181]
	v_pk_mul_f32 v[38:39], v[38:39], v[182:183]
	v_pk_mul_f32 v[36:37], v[36:37], v[180:181]
	v_pk_mul_f32 v[22:23], v[22:23], v[182:183]
	v_pk_mul_f32 v[20:21], v[20:21], v[180:181]
	v_pk_mul_f32 v[6:7], v[6:7], v[182:183]
	v_pk_mul_f32 v[4:5], v[4:5], v[180:181]
	v_pk_mul_f32 v[116:117], v[116:117], v[176:177]
	v_pk_mul_f32 v[102:103], v[102:103], v[178:179]
	v_pk_mul_f32 v[100:101], v[100:101], v[176:177]
	v_pk_mul_f32 v[82:83], v[82:83], v[178:179]
	v_pk_mul_f32 v[80:81], v[80:81], v[176:177]
	v_pk_mul_f32 v[66:67], v[66:67], v[178:179]
	v_pk_mul_f32 v[64:65], v[64:65], v[176:177]
	v_pk_mul_f32 v[50:51], v[50:51], v[178:179]
	v_pk_mul_f32 v[48:49], v[48:49], v[176:177]
	v_pk_mul_f32 v[34:35], v[34:35], v[178:179]
	v_pk_mul_f32 v[32:33], v[32:33], v[176:177]
	v_pk_mul_f32 v[18:19], v[18:19], v[178:179]
	v_pk_mul_f32 v[16:17], v[16:17], v[176:177]
	v_pk_mul_f32 v[2:3], v[2:3], v[178:179]
	v_pk_mul_f32 v[0:1], v[0:1], v[176:177]
